# scanC GLA tail: value-column permutation so gate loads and output stores are 16 bytes per lane
# speedup vs baseline: 1.0128x; 1.0029x over previous
.LBB0_1339:
	s_mul_hi_i32 s0, s67, 0x2aaaaaab
	s_lshr_b32 s1, s0, 31
	s_ashr_i32 s0, s0, 1
	s_add_i32 s20, s0, s1
	s_mul_i32 s0, s20, -12
	s_add_i32 s36, s67, s0
	s_mov_b64 s[0:1], -1
	s_cmp_gt_i32 s36, 7
	s_mul_i32 s37, s20, 0xfffffa00
	s_mul_i32 s68, s20, 0xe8000
	s_cbranch_scc0 .LBB0_1367
	s_add_i32 s0, s46, s37
	s_mul_i32 s1, s20, 0xfffff400
	s_addk_i32 s0, 0xe800
	s_add_i32 s38, s49, s1
	s_mov_b32 s1, s25
	s_add_i32 s24, s38, 0xffffe800
	s_lshl_b32 s21, s20, 6
	s_lshl_b64 s[40:41], s[0:1], 1
	s_add_u32 s40, s26, s40
	s_addc_u32 s41, s27, s41
	v_or_b32_e32 v20, s21, v135
	v_mov_b64_e32 v[2:3], s[40:41]
	v_mad_i64_i32 v[4:5], s[40:41], v20, s53, v[2:3]
	v_mov_b32_e32 v151, v137
	v_lshl_add_u64 v[4:5], v[4:5], 0, v[150:151]
	v_or_b32_e32 v21, 1, v20
	v_add_co_u32_e32 v4, vcc, s48, v4
	v_mad_i64_i32 v[6:7], s[40:41], v21, s53, v[2:3]
	s_nop 0
	v_addc_co_u32_e32 v5, vcc, 0, v5, vcc
	v_lshl_add_u64 v[6:7], v[6:7], 0, v[150:151]
	v_or_b32_e32 v31, 2, v20
	v_add_co_u32_e32 v6, vcc, s48, v6
	v_mad_i64_i32 v[8:9], s[40:41], v31, s53, v[2:3]
	s_nop 0
	v_addc_co_u32_e32 v7, vcc, 0, v7, vcc
	v_lshl_add_u64 v[8:9], v[8:9], 0, v[150:151]
	v_or_b32_e32 v32, 3, v20
	v_add_co_u32_e32 v8, vcc, s48, v8
	v_mad_i64_i32 v[10:11], s[40:41], v32, s53, v[2:3]
	s_nop 0
	v_addc_co_u32_e32 v9, vcc, 0, v9, vcc
	v_lshl_add_u64 v[10:11], v[10:11], 0, v[150:151]
	v_or_b32_e32 v33, 4, v20
	v_add_co_u32_e32 v10, vcc, s48, v10
	v_mad_i64_i32 v[12:13], s[40:41], v33, s53, v[2:3]
	s_nop 0
	v_addc_co_u32_e32 v11, vcc, 0, v11, vcc
	v_lshl_add_u64 v[12:13], v[12:13], 0, v[150:151]
	v_or_b32_e32 v34, 5, v20
	v_add_co_u32_e32 v12, vcc, s48, v12
	v_mad_i64_i32 v[14:15], s[40:41], v34, s53, v[2:3]
	s_nop 0
	v_addc_co_u32_e32 v13, vcc, 0, v13, vcc
	v_lshl_add_u64 v[14:15], v[14:15], 0, v[150:151]
	v_or_b32_e32 v35, 6, v20
	v_add_co_u32_e32 v14, vcc, s48, v14
	v_mad_i64_i32 v[16:17], s[40:41], v35, s53, v[2:3]
	s_nop 0
	v_addc_co_u32_e32 v15, vcc, 0, v15, vcc
	v_lshl_add_u64 v[16:17], v[16:17], 0, v[150:151]
	v_or_b32_e32 v36, 7, v20
	v_add_co_u32_e32 v16, vcc, s48, v16
	v_mad_i64_i32 v[18:19], s[40:41], v36, s53, v[2:3]
	s_nop 0
	v_addc_co_u32_e32 v17, vcc, 0, v17, vcc
	v_lshl_add_u64 v[18:19], v[18:19], 0, v[150:151]
	v_add_co_u32_e32 v18, vcc, s48, v18
	v_or_b32_e32 v37, 8, v20
	s_nop 0
	v_addc_co_u32_e32 v19, vcc, 0, v19, vcc
	global_load_ushort v89, v[4:5], off offset:2048
	s_nop 0
	global_load_ushort v90, v[6:7], off offset:2048
	s_nop 0
	global_load_ushort v91, v[8:9], off offset:2048
	s_nop 0
	global_load_ushort v92, v[10:11], off offset:2048
	global_load_ushort v93, v[12:13], off offset:2048
	s_nop 0
	global_load_ushort v94, v[14:15], off offset:2048
	global_load_ushort v95, v[16:17], off offset:2048
	global_load_ushort v128, v[18:19], off offset:2048
	v_mad_i64_i32 v[4:5], s[40:41], v37, s53, v[2:3]
	v_lshl_add_u64 v[4:5], v[4:5], 0, v[150:151]
	v_add_co_u32_e32 v4, vcc, s48, v4
	v_or_b32_e32 v38, 9, v20
	s_nop 0
	v_addc_co_u32_e32 v5, vcc, 0, v5, vcc
	global_load_ushort v129, v[4:5], off offset:2048
	v_mad_i64_i32 v[4:5], s[40:41], v38, s53, v[2:3]
	v_lshl_add_u64 v[4:5], v[4:5], 0, v[150:151]
	v_or_b32_e32 v39, 10, v20
	v_add_co_u32_e32 v4, vcc, s48, v4
	v_or_b32_e32 v40, 11, v20
	s_nop 0
	v_addc_co_u32_e32 v5, vcc, 0, v5, vcc
	v_or_b32_e32 v41, 12, v20
	v_or_b32_e32 v42, 13, v20
	v_or_b32_e32 v44, 14, v20
	v_mad_i64_i32 v[14:15], s[40:41], v44, s53, v[2:3]
	v_lshl_add_u64 v[14:15], v[14:15], 0, v[150:151]
	v_or_b32_e32 v46, 15, v20
	s_mul_hi_i32 s1, s21, 0x3a00
	s_add_u32 s33, s26, s68
	s_mov_b32 s39, s25
	v_add_u32_e32 v136, s0, v134
	s_addc_u32 s1, s27, s1
	v_readlane_b32 s72, v255, 13
	v_readlane_b32 s73, v255, 14
	v_readlane_b32 s74, v255, 15
	v_readlane_b32 s75, v255, 16
	v_readlane_b32 s76, v255, 17
	v_readlane_b32 s77, v255, 18
	v_readlane_b32 s78, v255, 19
	v_readlane_b32 s79, v255, 20
	v_readlane_b32 s80, v255, 21
	v_readlane_b32 s81, v255, 22
	v_readlane_b32 s82, v255, 23
	v_readlane_b32 s83, v255, 24
	v_readlane_b32 s84, v255, 25
	v_readlane_b32 s85, v255, 26
	s_mov_b64 s[72:73], s[76:77]
	s_mov_b64 s[74:75], s[78:79]
	s_mov_b64 s[76:77], s[80:81]
	s_mov_b64 s[78:79], s[82:83]
	v_mov_b32_e32 v153, v137
	v_mov_b32_e32 v155, v137
	v_mov_b32_e32 v149, v137
	v_readfirstlane_b32 s69, v0
	v_mov_b32_e32 v157, v137
	v_readlane_b32 s86, v255, 27
	v_readlane_b32 s87, v255, 28
	s_mov_b64 s[80:81], s[84:85]
	v_mad_i64_i32 v[6:7], s[40:41], v39, s53, v[2:3]
	v_lshl_add_u64 v[6:7], v[6:7], 0, v[150:151]
	v_add_co_u32_e32 v6, vcc, s48, v6
	v_mad_i64_i32 v[8:9], s[40:41], v40, s53, v[2:3]
	s_nop 0
	v_addc_co_u32_e32 v7, vcc, 0, v7, vcc
	v_lshl_add_u64 v[8:9], v[8:9], 0, v[150:151]
	v_add_co_u32_e32 v8, vcc, s48, v8
	v_mad_i64_i32 v[10:11], s[40:41], v41, s53, v[2:3]
	s_nop 0
	v_addc_co_u32_e32 v9, vcc, 0, v9, vcc
	v_lshl_add_u64 v[10:11], v[10:11], 0, v[150:151]
	v_add_co_u32_e32 v10, vcc, s48, v10
	v_mad_i64_i32 v[12:13], s[40:41], v42, s53, v[2:3]
	s_nop 0
	v_addc_co_u32_e32 v11, vcc, 0, v11, vcc
	v_lshl_add_u64 v[12:13], v[12:13], 0, v[150:151]
	v_add_co_u32_e32 v12, vcc, s48, v12
	v_mad_i64_i32 v[2:3], s[40:41], v46, s53, v[2:3]
	s_nop 0
	v_addc_co_u32_e32 v13, vcc, 0, v13, vcc
	v_add_co_u32_e32 v14, vcc, s48, v14
	v_lshl_add_u64 v[2:3], v[2:3], 0, v[150:151]
	s_nop 0
	v_addc_co_u32_e32 v15, vcc, 0, v15, vcc
	v_add_co_u32_e32 v2, vcc, s48, v2
	s_lshl_b64 s[40:41], s[38:39], 1
	s_nop 0
	v_addc_co_u32_e32 v3, vcc, 0, v3, vcc
	global_load_ushort v43, v[4:5], off offset:2048
	global_load_ushort v45, v[6:7], off offset:2048
	global_load_ushort v47, v[8:9], off offset:2048
	global_load_ushort v48, v[10:11], off offset:2048
	global_load_ushort v52, v[12:13], off offset:2048
	global_load_ushort v54, v[14:15], off offset:2048
	global_load_ushort v59, v[2:3], off offset:2048
	v_lshl_add_u64 v[10:11], v[136:137], 1, s[92:93]
	s_add_u32 s40, s33, s40
	v_lshl_add_u64 v[72:73], v[10:11], 0, s[28:29]
	s_addc_u32 s41, s1, s41
	v_mad_i64_i32 v[10:11], s[0:1], v20, s53, v[72:73]
	v_mad_i64_i32 v[12:13], s[0:1], v21, s53, v[72:73]
	v_mad_i64_i32 v[14:15], s[0:1], v31, s53, v[72:73]
	v_mad_i64_i32 v[16:17], s[0:1], v32, s53, v[72:73]
	v_mad_i64_i32 v[18:19], s[0:1], v33, s53, v[72:73]
	v_mad_i64_i32 v[20:21], s[0:1], v34, s53, v[72:73]
	v_mad_i64_i32 v[32:33], s[0:1], v35, s53, v[72:73]
	v_mad_i64_i32 v[34:35], s[0:1], v36, s53, v[72:73]
	v_readfirstlane_b32 s0, v1
	s_lshl_b32 s0, s0, 4
	v_lshlrev_b64 v[2:3], 2, v[136:137]
	s_add_i32 s0, s0, s21
	v_lshl_add_u64 v[4:5], s[76:77], 0, v[2:3]
	s_ashr_i32 s1, s0, 31
	v_add_co_u32_e32 v6, vcc, s48, v4
	v_lshl_add_u64 v[2:3], s[78:79], 0, v[2:3]
	s_lshl_b64 s[0:1], s[0:1], 6
	v_addc_co_u32_e32 v7, vcc, 0, v5, vcc
	global_load_dword v51, v[4:5], off
	global_load_dword v50, v[4:5], off offset:2048
	global_load_dword v49, v[6:7], off offset:2048
	global_load_ushort v60, v[10:11], off
	global_load_ushort v64, v[12:13], off
	global_load_ushort v71, v[14:15], off
	global_load_ushort v74, v[16:17], off
	global_load_ushort v75, v[18:19], off
	global_load_ushort v76, v[20:21], off
	global_load_ushort v77, v[32:33], off
	global_load_ushort v78, v[34:35], off
	global_load_dword v53, v[2:3], off
	v_lshl_add_u64 v[2:3], v[144:145], 0, s[0:1]
	global_load_dwordx4 v[18:21], v[2:3], off
	v_add_co_u32_e32 v8, vcc, s54, v4
	s_bfe_u32 s71, s69, 0x20006
	s_nop 0
	v_addc_co_u32_e32 v9, vcc, 0, v5, vcc
	v_add_co_u32_e32 v6, vcc, s55, v4
	global_load_dword v70, v[8:9], off offset:-4096
	global_load_dword v68, v[8:9], off
	global_load_dword v65, v[8:9], off offset:2048
	v_addc_co_u32_e32 v7, vcc, 0, v5, vcc
	v_add_co_u32_e32 v2, vcc, s56, v4
	s_lshl_b32 s33, s71, 4
	s_nop 0
	v_addc_co_u32_e32 v3, vcc, 0, v5, vcc
	v_add_co_u32_e32 v8, vcc, s57, v4
	s_nop 0
	v_addc_co_u32_e32 v9, vcc, 0, v5, vcc
	v_add_co_u32_e32 v10, vcc, s58, v4
	s_nop 0
	v_addc_co_u32_e32 v11, vcc, 0, v5, vcc
	global_load_dword v66, v[6:7], off offset:2048
	global_load_dword v69, v[2:3], off offset:-4096
	global_load_dword v67, v[2:3], off
	global_load_dword v62, v[2:3], off offset:2048
	global_load_dword v61, v[10:11], off offset:-4096
	global_load_dword v58, v[10:11], off
	global_load_dword v56, v[10:11], off offset:2048
	v_add_co_u32_e32 v2, vcc, s59, v4
	v_mad_i64_i32 v[6:7], s[0:1], v39, s53, v[72:73]
	s_nop 0
	v_addc_co_u32_e32 v3, vcc, 0, v5, vcc
	global_load_dword v63, v[8:9], off offset:2048
	global_load_dword v57, v[2:3], off
	global_load_dword v55, v[2:3], off offset:2048
	v_mad_i64_i32 v[2:3], s[0:1], v37, s53, v[72:73]
	v_mad_i64_i32 v[4:5], s[0:1], v38, s53, v[72:73]
	global_load_ushort v38, v[2:3], off
	global_load_ushort v79, v[4:5], off
	global_load_ushort v80, v[6:7], off
	v_mad_i64_i32 v[2:3], s[0:1], v40, s53, v[72:73]
	v_mad_i64_i32 v[4:5], s[0:1], v41, s53, v[72:73]
	global_load_ushort v40, v[2:3], off
	global_load_ushort v81, v[4:5], off
	v_lshl_add_u64 v[2:3], s[40:41], 0, v[152:153]
	s_mov_b64 s[0:1], 0x3a00
	s_waitcnt vmcnt(37)
	v_lshlrev_b32_e32 v30, 16, v89
	v_lshlrev_b32_e32 v29, 16, v90
	v_lshlrev_b32_e32 v28, 16, v91
	v_lshlrev_b32_e32 v27, 16, v92
	v_lshlrev_b32_e32 v25, 16, v93
	v_lshlrev_b32_e32 v24, 16, v94
	v_lshlrev_b32_e32 v23, 16, v95
	v_lshlrev_b32_e32 v22, 16, v128
	v_lshlrev_b32_e32 v26, 16, v129
	v_mul_f32_e32 v30, 0x3db504f3, v30
	v_mul_f32_e32 v29, 0x3db504f3, v29
	v_lshlrev_b32_e32 v37, 16, v43
	s_waitcnt vmcnt(36)
	v_lshlrev_b32_e32 v36, 16, v45
	s_waitcnt vmcnt(35)
	v_lshlrev_b32_e32 v35, 16, v47
	v_lshl_add_u64 v[4:5], v[2:3], 0, s[0:1]
	s_waitcnt vmcnt(34)
	v_lshlrev_b32_e32 v34, 16, v48
	v_lshl_add_u64 v[6:7], v[2:3], 0, v[154:155]
	v_lshl_add_u64 v[8:9], v[4:5], 0, v[154:155]
	global_load_dwordx4 v[10:13], v[6:7], off
	global_load_dwordx4 v[14:17], v[8:9], off
	v_lshl_add_u64 v[2:3], v[2:3], 0, v[148:149]
	v_lshl_add_u64 v[6:7], v[4:5], 0, v[148:149]
	s_waitcnt vmcnt(35)
	v_lshlrev_b32_e32 v33, 16, v52
	s_waitcnt vmcnt(34)
	v_lshlrev_b32_e32 v32, 16, v54
	s_waitcnt vmcnt(33)
	v_lshlrev_b32_e32 v31, 16, v59
	global_load_dwordx4 v[2:5], v[2:3], off
	s_nop 0
	global_load_dwordx4 v[6:9], v[6:7], off
	v_or_b32_e32 v149, s33, v139
	v_mul_f32_e32 v28, 0x3db504f3, v28
	v_mul_f32_e32 v27, 0x3db504f3, v27
	v_mul_f32_e32 v25, 0x3db504f3, v25
	v_mul_f32_e32 v24, 0x3db504f3, v24
	v_mul_f32_e32 v23, 0x3db504f3, v23
	v_mul_f32_e32 v22, 0x3db504f3, v22
	v_mul_f32_e32 v26, 0x3db504f3, v26
	v_mul_f32_e32 v36, 0x3db504f3, v36
	v_mul_f32_e32 v35, 0x3db504f3, v35
	s_waitcnt vmcnt(31)
	v_lshlrev_b32_e32 v54, 16, v60
	s_waitcnt vmcnt(30)
	v_lshlrev_b32_e32 v52, 16, v64
	s_waitcnt vmcnt(29)
	v_lshlrev_b32_e32 v48, 16, v71
	s_waitcnt vmcnt(28)
	v_lshlrev_b32_e32 v47, 16, v74
	s_waitcnt vmcnt(27)
	v_lshlrev_b32_e32 v45, 16, v75
	s_waitcnt vmcnt(26)
	v_lshlrev_b32_e32 v43, 16, v76
	s_waitcnt vmcnt(25)
	v_lshlrev_b32_e32 v41, 16, v77
	v_mad_i64_i32 v[74:75], s[0:1], v42, s53, v[72:73]
	v_mad_i64_i32 v[76:77], s[0:1], v44, s53, v[72:73]
	v_mad_i64_i32 v[72:73], s[0:1], v46, s53, v[72:73]
	s_waitcnt vmcnt(22)
	v_readlane_b32 s0, v18, 0
	global_load_ushort v64, v[74:75], off
	global_load_ushort v59, v[76:77], off
	global_load_ushort v60, v[72:73], off
	v_fma_f32 v71, s0, v51, v53
	v_readlane_b32 s0, v19, 0
	v_lshlrev_b32_e32 v39, 16, v78
	v_mul_f32_e32 v34, 0x3db504f3, v34
	v_fmac_f32_e32 v71, s0, v50
	v_readlane_b32 s0, v20, 0
	v_mul_f32_e32 v33, 0x3db504f3, v33
	v_mul_f32_e32 v32, 0x3db504f3, v32
	s_waitcnt vmcnt(24)
	v_fmac_f32_e32 v71, s0, v70
	v_readlane_b32 s0, v21, 0
	v_mul_f32_e32 v31, 0x3db504f3, v31
	s_waitcnt vmcnt(11)
	v_lshlrev_b32_e32 v46, 16, v38
	v_fmac_f32_e32 v71, s0, v49
	v_readlane_b32 s0, v18, 1
	s_waitcnt vmcnt(10)
	v_lshlrev_b32_e32 v44, 16, v79
	s_waitcnt vmcnt(8)
	v_lshlrev_b32_e32 v40, 16, v40
	v_fmac_f32_e32 v71, s0, v68
	v_readlane_b32 s0, v19, 1
	s_waitcnt vmcnt(1)
	v_lshlrev_b32_e32 v59, 16, v59
	v_fmac_f32_e32 v71, s0, v65
	v_readlane_b32 s0, v20, 1
	s_waitcnt vmcnt(0)
	v_lshlrev_b32_e32 v60, 16, v60
	v_fmac_f32_e32 v71, s0, v69
	v_readlane_b32 s0, v21, 1
	s_nop 1
	v_fmac_f32_e32 v71, s0, v66
	v_readlane_b32 s0, v18, 2
	s_nop 1
	v_fmac_f32_e32 v71, s0, v67
	v_readlane_b32 s0, v19, 2
	s_nop 1
	v_fmac_f32_e32 v71, s0, v62
	v_readlane_b32 s0, v20, 2
	s_nop 1
	v_fmac_f32_e32 v71, s0, v61
	v_readlane_b32 s0, v21, 2
	s_nop 1
	v_fmac_f32_e32 v71, s0, v63
	v_readlane_b32 s0, v18, 3
	s_nop 1
	v_fmac_f32_e32 v71, s0, v58
	v_readlane_b32 s0, v19, 3
	s_nop 1
	v_fmac_f32_e32 v71, s0, v56
	v_readlane_b32 s0, v20, 3
	s_nop 1
	v_fmac_f32_e32 v71, s0, v57
	v_readlane_b32 s0, v21, 3
	s_nop 1
	v_fmac_f32_e32 v71, s0, v55
	v_readlane_b32 s0, v18, 4
	v_mul_f32_e64 v42, |v71|, s60
	v_exp_f32_e32 v72, v42
	v_fma_f32 v74, s0, v51, v53
	v_readlane_b32 s0, v19, 4
	v_min_f32_e32 v71, 0, v71
	v_add_f32_e32 v38, 1.0, v72
	v_fmac_f32_e32 v74, s0, v50
	v_readlane_b32 s0, v20, 4
	v_cmp_gt_f32_e32 vcc, s61, v38
	v_lshlrev_b32_e32 v42, 16, v80
	v_fmac_f32_e32 v74, s0, v70
	v_readlane_b32 s0, v21, 4
	v_cndmask_b32_e64 v72, 0, 32, vcc
	v_ldexp_f32 v38, v38, v72
	v_fmac_f32_e32 v74, s0, v49
	v_readlane_b32 s0, v18, 5
	v_log_f32_e32 v72, v38
	v_lshlrev_b32_e32 v38, 16, v81
	v_fmac_f32_e32 v74, s0, v68
	v_readlane_b32 s0, v19, 5
	v_mul_f32_e32 v73, 0x3f317217, v72
	v_fma_f32 v73, v72, s62, -v73
	v_fmac_f32_e32 v74, s0, v65
	v_readlane_b32 s0, v20, 5
	v_fmac_f32_e32 v73, 0x3377d1cf, v72
	v_fmac_f32_e32 v73, 0x3f317217, v72
	v_fmac_f32_e32 v74, s0, v69
	v_readlane_b32 s0, v21, 5
	s_nop 1
	v_fmac_f32_e32 v74, s0, v66
	v_readlane_b32 s0, v18, 6
	s_nop 1
	v_fmac_f32_e32 v74, s0, v67
	v_readlane_b32 s0, v19, 6
	s_nop 1
	v_fmac_f32_e32 v74, s0, v62
	v_readlane_b32 s0, v20, 6
	s_nop 1
	v_fmac_f32_e32 v74, s0, v61
	v_readlane_b32 s0, v21, 6
	s_nop 1
	v_fmac_f32_e32 v74, s0, v63
	v_readlane_b32 s0, v18, 7
	s_nop 1
	v_fmac_f32_e32 v74, s0, v58
	v_readlane_b32 s0, v19, 7
	s_nop 1
	v_fmac_f32_e32 v74, s0, v56
	v_readlane_b32 s0, v20, 7
	s_nop 1
	v_fmac_f32_e32 v74, s0, v57
	v_readlane_b32 s0, v21, 7
	s_nop 1
	v_fmac_f32_e32 v74, s0, v55
	v_mul_f32_e64 v75, |v74|, s60
	v_exp_f32_e32 v75, v75
	v_cmp_lt_f32_e64 s[0:1], |v72|, s63
	s_nop 1
	v_cndmask_b32_e64 v72, v72, v73, s[0:1]
	v_cndmask_b32_e32 v73, 0, v195, vcc
	v_sub_f32_e32 v72, v72, v73
	v_add_f32_e32 v73, 1.0, v75
	v_cmp_gt_f32_e32 vcc, s61, v73
	v_readlane_b32 s0, v18, 8
	v_sub_f32_e32 v71, v71, v72
	v_cndmask_b32_e64 v75, 0, 32, vcc
	v_ldexp_f32 v73, v73, v75
	v_fma_f32 v75, s0, v51, v53
	v_readlane_b32 s0, v19, 8
	v_log_f32_e32 v73, v73
	v_min_f32_e32 v72, 0, v74
	v_fmac_f32_e32 v75, s0, v50
	v_readlane_b32 s0, v20, 8
	v_mul_f32_e32 v74, 0x3f317217, v73
	v_fma_f32 v74, v73, s62, -v74
	v_fmac_f32_e32 v75, s0, v70
	v_readlane_b32 s0, v21, 8
	v_fmac_f32_e32 v74, 0x3377d1cf, v73
	v_fmac_f32_e32 v74, 0x3f317217, v73
	v_fmac_f32_e32 v75, s0, v49
	v_readlane_b32 s0, v18, 9
	v_fma_f32 v71, v71, s64, 0
	s_nop 0
	v_fmac_f32_e32 v75, s0, v68
	v_readlane_b32 s0, v19, 9
	s_nop 1
	v_fmac_f32_e32 v75, s0, v65
	v_readlane_b32 s0, v20, 9
	s_nop 1
	v_fmac_f32_e32 v75, s0, v69
	v_readlane_b32 s0, v21, 9
	s_nop 1
	v_fmac_f32_e32 v75, s0, v66
	v_readlane_b32 s0, v18, 10
	s_nop 1
	v_fmac_f32_e32 v75, s0, v67
	v_readlane_b32 s0, v19, 10
	s_nop 1
	v_fmac_f32_e32 v75, s0, v62
	v_readlane_b32 s0, v20, 10
	s_nop 1
	v_fmac_f32_e32 v75, s0, v61
	v_readlane_b32 s0, v21, 10
	s_nop 1
	v_fmac_f32_e32 v75, s0, v63
	v_readlane_b32 s0, v18, 11
	s_nop 1
	v_fmac_f32_e32 v75, s0, v58
	v_readlane_b32 s0, v19, 11
	s_nop 1
	v_fmac_f32_e32 v75, s0, v56
	v_readlane_b32 s0, v20, 11
	s_nop 1
	v_fmac_f32_e32 v75, s0, v57
	v_readlane_b32 s0, v21, 11
	s_nop 1
	v_fmac_f32_e32 v75, s0, v55
	v_mul_f32_e64 v76, |v75|, s60
	v_exp_f32_e32 v76, v76
	v_cmp_lt_f32_e64 s[0:1], |v73|, s63
	s_nop 1
	v_cndmask_b32_e64 v73, v73, v74, s[0:1]
	v_cndmask_b32_e32 v74, 0, v195, vcc
	v_sub_f32_e32 v73, v73, v74
	v_add_f32_e32 v74, 1.0, v76
	v_cmp_gt_f32_e32 vcc, s61, v74
	v_readlane_b32 s0, v18, 12
	v_sub_f32_e32 v72, v72, v73
	v_cndmask_b32_e64 v76, 0, 32, vcc
	v_ldexp_f32 v74, v74, v76
	v_fma_f32 v76, s0, v51, v53
	v_readlane_b32 s0, v19, 12
	v_log_f32_e32 v74, v74
	v_min_f32_e32 v73, 0, v75
	v_fmac_f32_e32 v76, s0, v50
	v_readlane_b32 s0, v20, 12
	v_mul_f32_e32 v75, 0x3f317217, v74
	v_fma_f32 v75, v74, s62, -v75
	v_fmac_f32_e32 v76, s0, v70
	v_readlane_b32 s0, v21, 12
	v_fmac_f32_e32 v75, 0x3377d1cf, v74
	v_fmac_f32_e32 v75, 0x3f317217, v74
	v_fmac_f32_e32 v76, s0, v49
	v_readlane_b32 s0, v18, 13
	v_fmamk_f32 v72, v72, 0x3d800000, v71
	s_nop 0
	v_fmac_f32_e32 v76, s0, v68
	v_readlane_b32 s0, v19, 13
	s_nop 1
	v_fmac_f32_e32 v76, s0, v65
	v_readlane_b32 s0, v20, 13
	s_nop 1
	v_fmac_f32_e32 v76, s0, v69
	v_readlane_b32 s0, v21, 13
	s_nop 1
	v_fmac_f32_e32 v76, s0, v66
	v_readlane_b32 s0, v18, 14
	s_nop 1
	v_fmac_f32_e32 v76, s0, v67
	v_readlane_b32 s0, v19, 14
	s_nop 1
	v_fmac_f32_e32 v76, s0, v62
	v_readlane_b32 s0, v20, 14
	s_nop 1
	v_fmac_f32_e32 v76, s0, v61
	v_readlane_b32 s0, v21, 14
	s_nop 1
	v_fmac_f32_e32 v76, s0, v63
	v_readlane_b32 s0, v18, 15
	s_nop 1
	v_fmac_f32_e32 v76, s0, v58
	v_readlane_b32 s0, v19, 15
	s_nop 1
	v_fmac_f32_e32 v76, s0, v56
	v_readlane_b32 s0, v20, 15
	s_nop 1
	v_fmac_f32_e32 v76, s0, v57
	v_readlane_b32 s0, v21, 15
	s_nop 1
	v_fmac_f32_e32 v76, s0, v55
	v_mul_f32_e64 v77, |v76|, s60
	v_exp_f32_e32 v77, v77
	v_cmp_lt_f32_e64 s[0:1], |v74|, s63
	s_nop 1
	v_cndmask_b32_e64 v74, v74, v75, s[0:1]
	v_cndmask_b32_e32 v75, 0, v195, vcc
	v_sub_f32_e32 v74, v74, v75
	v_add_f32_e32 v75, 1.0, v77
	v_cmp_gt_f32_e32 vcc, s61, v75
	v_readlane_b32 s0, v18, 16
	v_sub_f32_e32 v73, v73, v74
	v_cndmask_b32_e64 v77, 0, 32, vcc
	v_ldexp_f32 v75, v75, v77
	v_fma_f32 v77, s0, v51, v53
	v_readlane_b32 s0, v19, 16
	v_log_f32_e32 v75, v75
	v_min_f32_e32 v74, 0, v76
	v_fmac_f32_e32 v77, s0, v50
	v_readlane_b32 s0, v20, 16
	v_mul_f32_e32 v76, 0x3f317217, v75
	v_fma_f32 v76, v75, s62, -v76
	v_fmac_f32_e32 v77, s0, v70
	v_readlane_b32 s0, v21, 16
	v_fmac_f32_e32 v76, 0x3377d1cf, v75
	v_fmac_f32_e32 v76, 0x3f317217, v75
	v_fmac_f32_e32 v77, s0, v49
	v_readlane_b32 s0, v18, 17
	v_fmamk_f32 v73, v73, 0x3d800000, v72
	s_nop 0
	v_fmac_f32_e32 v77, s0, v68
	v_readlane_b32 s0, v19, 17
	s_nop 1
	v_fmac_f32_e32 v77, s0, v65
	v_readlane_b32 s0, v20, 17
	s_nop 1
	v_fmac_f32_e32 v77, s0, v69
	v_readlane_b32 s0, v21, 17
	s_nop 1
	v_fmac_f32_e32 v77, s0, v66
	v_readlane_b32 s0, v18, 18
	s_nop 1
	v_fmac_f32_e32 v77, s0, v67
	v_readlane_b32 s0, v19, 18
	s_nop 1
	v_fmac_f32_e32 v77, s0, v62
	v_readlane_b32 s0, v20, 18
	s_nop 1
	v_fmac_f32_e32 v77, s0, v61
	v_readlane_b32 s0, v21, 18
	s_nop 1
	v_fmac_f32_e32 v77, s0, v63
	v_readlane_b32 s0, v18, 19
	s_nop 1
	v_fmac_f32_e32 v77, s0, v58
	v_readlane_b32 s0, v19, 19
	s_nop 1
	v_fmac_f32_e32 v77, s0, v56
	v_readlane_b32 s0, v20, 19
	s_nop 1
	v_fmac_f32_e32 v77, s0, v57
	v_readlane_b32 s0, v21, 19
	s_nop 1
	v_fmac_f32_e32 v77, s0, v55
	v_mul_f32_e64 v78, |v77|, s60
	v_exp_f32_e32 v78, v78
	v_cmp_lt_f32_e64 s[0:1], |v75|, s63
	s_nop 1
	v_cndmask_b32_e64 v75, v75, v76, s[0:1]
	v_cndmask_b32_e32 v76, 0, v195, vcc
	v_sub_f32_e32 v75, v75, v76
	v_add_f32_e32 v76, 1.0, v78
	v_cmp_gt_f32_e32 vcc, s61, v76
	v_readlane_b32 s0, v18, 20
	v_sub_f32_e32 v74, v74, v75
	v_cndmask_b32_e64 v78, 0, 32, vcc
	v_ldexp_f32 v76, v76, v78
	v_fma_f32 v78, s0, v51, v53
	v_readlane_b32 s0, v19, 20
	v_log_f32_e32 v76, v76
	v_min_f32_e32 v75, 0, v77
	v_fmac_f32_e32 v78, s0, v50
	v_readlane_b32 s0, v20, 20
	v_mul_f32_e32 v77, 0x3f317217, v76
	v_fma_f32 v77, v76, s62, -v77
	v_fmac_f32_e32 v78, s0, v70
	v_readlane_b32 s0, v21, 20
	v_fmac_f32_e32 v77, 0x3377d1cf, v76
	v_fmac_f32_e32 v77, 0x3f317217, v76
	v_fmac_f32_e32 v78, s0, v49
	v_readlane_b32 s0, v18, 21
	v_fmamk_f32 v74, v74, 0x3d800000, v73
	s_nop 0
	v_fmac_f32_e32 v78, s0, v68
	v_readlane_b32 s0, v19, 21
	s_nop 1
	v_fmac_f32_e32 v78, s0, v65
	v_readlane_b32 s0, v20, 21
	s_nop 1
	v_fmac_f32_e32 v78, s0, v69
	v_readlane_b32 s0, v21, 21
	s_nop 1
	v_fmac_f32_e32 v78, s0, v66
	v_readlane_b32 s0, v18, 22
	s_nop 1
	v_fmac_f32_e32 v78, s0, v67
	v_readlane_b32 s0, v19, 22
	s_nop 1
	v_fmac_f32_e32 v78, s0, v62
	v_readlane_b32 s0, v20, 22
	s_nop 1
	v_fmac_f32_e32 v78, s0, v61
	v_readlane_b32 s0, v21, 22
	s_nop 1
	v_fmac_f32_e32 v78, s0, v63
	v_readlane_b32 s0, v18, 23
	s_nop 1
	v_fmac_f32_e32 v78, s0, v58
	v_readlane_b32 s0, v19, 23
	s_nop 1
	v_fmac_f32_e32 v78, s0, v56
	v_readlane_b32 s0, v20, 23
	s_nop 1
	v_fmac_f32_e32 v78, s0, v57
	v_readlane_b32 s0, v21, 23
	s_nop 1
	v_fmac_f32_e32 v78, s0, v55
	v_mul_f32_e64 v79, |v78|, s60
	v_exp_f32_e32 v79, v79
	v_cmp_lt_f32_e64 s[0:1], |v76|, s63
	s_nop 1
	v_cndmask_b32_e64 v76, v76, v77, s[0:1]
	v_cndmask_b32_e32 v77, 0, v195, vcc
	v_sub_f32_e32 v76, v76, v77
	v_add_f32_e32 v77, 1.0, v79
	v_cmp_gt_f32_e32 vcc, s61, v77
	v_readlane_b32 s0, v18, 24
	v_sub_f32_e32 v75, v75, v76
	v_cndmask_b32_e64 v79, 0, 32, vcc
	v_ldexp_f32 v77, v77, v79
	v_fma_f32 v79, s0, v51, v53
	v_readlane_b32 s0, v19, 24
	v_log_f32_e32 v77, v77
	v_min_f32_e32 v76, 0, v78
	v_fmac_f32_e32 v79, s0, v50
	v_readlane_b32 s0, v20, 24
	v_mul_f32_e32 v78, 0x3f317217, v77
	v_fma_f32 v78, v77, s62, -v78
	v_fmac_f32_e32 v79, s0, v70
	v_readlane_b32 s0, v21, 24
	v_fmac_f32_e32 v78, 0x3377d1cf, v77
	v_fmac_f32_e32 v78, 0x3f317217, v77
	v_fmac_f32_e32 v79, s0, v49
	v_readlane_b32 s0, v18, 25
	v_fmamk_f32 v75, v75, 0x3d800000, v74
	s_nop 0
	v_fmac_f32_e32 v79, s0, v68
	v_readlane_b32 s0, v19, 25
	s_nop 1
	v_fmac_f32_e32 v79, s0, v65
	v_readlane_b32 s0, v20, 25
	s_nop 1
	v_fmac_f32_e32 v79, s0, v69
	v_readlane_b32 s0, v21, 25
	s_nop 1
	v_fmac_f32_e32 v79, s0, v66
	v_readlane_b32 s0, v18, 26
	s_nop 1
	v_fmac_f32_e32 v79, s0, v67
	v_readlane_b32 s0, v19, 26
	s_nop 1
	v_fmac_f32_e32 v79, s0, v62
	v_readlane_b32 s0, v20, 26
	s_nop 1
	v_fmac_f32_e32 v79, s0, v61
	v_readlane_b32 s0, v21, 26
	s_nop 1
	v_fmac_f32_e32 v79, s0, v63
	v_readlane_b32 s0, v18, 27
	s_nop 1
	v_fmac_f32_e32 v79, s0, v58
	v_readlane_b32 s0, v19, 27
	s_nop 1
	v_fmac_f32_e32 v79, s0, v56
	v_readlane_b32 s0, v20, 27
	s_nop 1
	v_fmac_f32_e32 v79, s0, v57
	v_readlane_b32 s0, v21, 27
	s_nop 1
	v_fmac_f32_e32 v79, s0, v55
	v_mul_f32_e64 v80, |v79|, s60
	v_exp_f32_e32 v80, v80
	v_cmp_lt_f32_e64 s[0:1], |v77|, s63
	s_nop 1
	v_cndmask_b32_e64 v77, v77, v78, s[0:1]
	v_cndmask_b32_e32 v78, 0, v195, vcc
	v_sub_f32_e32 v77, v77, v78
	v_add_f32_e32 v78, 1.0, v80
	v_cmp_gt_f32_e32 vcc, s61, v78
	v_readlane_b32 s0, v18, 28
	v_sub_f32_e32 v76, v76, v77
	v_cndmask_b32_e64 v80, 0, 32, vcc
	v_ldexp_f32 v78, v78, v80
	v_fma_f32 v80, s0, v51, v53
	v_readlane_b32 s0, v19, 28
	v_log_f32_e32 v78, v78
	v_min_f32_e32 v77, 0, v79
	v_fmac_f32_e32 v80, s0, v50
	v_readlane_b32 s0, v20, 28
	v_mul_f32_e32 v79, 0x3f317217, v78
	v_fma_f32 v79, v78, s62, -v79
	v_fmac_f32_e32 v80, s0, v70
	v_readlane_b32 s0, v21, 28
	v_fmac_f32_e32 v79, 0x3377d1cf, v78
	v_fmac_f32_e32 v79, 0x3f317217, v78
	v_fmac_f32_e32 v80, s0, v49
	v_readlane_b32 s0, v18, 29
	v_fmamk_f32 v76, v76, 0x3d800000, v75
	s_nop 0
	v_fmac_f32_e32 v80, s0, v68
	v_readlane_b32 s0, v19, 29
	s_nop 1
	v_fmac_f32_e32 v80, s0, v65
	v_readlane_b32 s0, v20, 29
	s_nop 1
	v_fmac_f32_e32 v80, s0, v69
	v_readlane_b32 s0, v21, 29
	s_nop 1
	v_fmac_f32_e32 v80, s0, v66
	v_readlane_b32 s0, v18, 30
	s_nop 1
	v_fmac_f32_e32 v80, s0, v67
	v_readlane_b32 s0, v19, 30
	s_nop 1
	v_fmac_f32_e32 v80, s0, v62
	v_readlane_b32 s0, v20, 30
	s_nop 1
	v_fmac_f32_e32 v80, s0, v61
	v_readlane_b32 s0, v21, 30
	s_nop 1
	v_fmac_f32_e32 v80, s0, v63
	v_readlane_b32 s0, v18, 31
	s_nop 1
	v_fmac_f32_e32 v80, s0, v58
	v_readlane_b32 s0, v19, 31
	s_nop 1
	v_fmac_f32_e32 v80, s0, v56
	v_readlane_b32 s0, v20, 31
	s_nop 1
	v_fmac_f32_e32 v80, s0, v57
	v_readlane_b32 s0, v21, 31
	s_nop 1
	v_fmac_f32_e32 v80, s0, v55
	v_mul_f32_e64 v81, |v80|, s60
	v_exp_f32_e32 v81, v81
	v_cmp_lt_f32_e64 s[0:1], |v78|, s63
	s_nop 1
	v_cndmask_b32_e64 v78, v78, v79, s[0:1]
	v_cndmask_b32_e32 v79, 0, v195, vcc
	v_sub_f32_e32 v78, v78, v79
	v_add_f32_e32 v79, 1.0, v81
	v_cmp_gt_f32_e32 vcc, s61, v79
	v_readlane_b32 s0, v18, 32
	v_sub_f32_e32 v77, v77, v78
	v_cndmask_b32_e64 v81, 0, 32, vcc
	v_ldexp_f32 v79, v79, v81
	v_fma_f32 v81, s0, v51, v53
	v_readlane_b32 s0, v19, 32
	v_log_f32_e32 v79, v79
	v_min_f32_e32 v78, 0, v80
	v_fmac_f32_e32 v81, s0, v50
	v_readlane_b32 s0, v20, 32
	v_mul_f32_e32 v80, 0x3f317217, v79
	v_fma_f32 v80, v79, s62, -v80
	v_fmac_f32_e32 v81, s0, v70
	v_readlane_b32 s0, v21, 32
	v_fmac_f32_e32 v80, 0x3377d1cf, v79
	v_fmac_f32_e32 v80, 0x3f317217, v79
	v_fmac_f32_e32 v81, s0, v49
	v_readlane_b32 s0, v18, 33
	v_fmamk_f32 v77, v77, 0x3d800000, v76
	s_nop 0
	v_fmac_f32_e32 v81, s0, v68
	v_readlane_b32 s0, v19, 33
	s_nop 1
	v_fmac_f32_e32 v81, s0, v65
	v_readlane_b32 s0, v20, 33
	s_nop 1
	v_fmac_f32_e32 v81, s0, v69
	v_readlane_b32 s0, v21, 33
	s_nop 1
	v_fmac_f32_e32 v81, s0, v66
	v_readlane_b32 s0, v18, 34
	s_nop 1
	v_fmac_f32_e32 v81, s0, v67
	v_readlane_b32 s0, v19, 34
	s_nop 1
	v_fmac_f32_e32 v81, s0, v62
	v_readlane_b32 s0, v20, 34
	s_nop 1
	v_fmac_f32_e32 v81, s0, v61
	v_readlane_b32 s0, v21, 34
	s_nop 1
	v_fmac_f32_e32 v81, s0, v63
	v_readlane_b32 s0, v18, 35
	s_nop 1
	v_fmac_f32_e32 v81, s0, v58
	v_readlane_b32 s0, v19, 35
	s_nop 1
	v_fmac_f32_e32 v81, s0, v56
	v_readlane_b32 s0, v20, 35
	s_nop 1
	v_fmac_f32_e32 v81, s0, v57
	v_readlane_b32 s0, v21, 35
	s_nop 1
	v_fmac_f32_e32 v81, s0, v55
	v_mul_f32_e64 v82, |v81|, s60
	v_exp_f32_e32 v82, v82
	v_cmp_lt_f32_e64 s[0:1], |v79|, s63
	s_nop 1
	v_cndmask_b32_e64 v79, v79, v80, s[0:1]
	v_cndmask_b32_e32 v80, 0, v195, vcc
	v_sub_f32_e32 v79, v79, v80
	v_add_f32_e32 v80, 1.0, v82
	v_cmp_gt_f32_e32 vcc, s61, v80
	v_readlane_b32 s0, v18, 36
	v_sub_f32_e32 v78, v78, v79
	v_cndmask_b32_e64 v82, 0, 32, vcc
	v_ldexp_f32 v80, v80, v82
	v_fma_f32 v82, s0, v51, v53
	v_readlane_b32 s0, v19, 36
	v_log_f32_e32 v80, v80
	v_min_f32_e32 v79, 0, v81
	v_fmac_f32_e32 v82, s0, v50
	v_readlane_b32 s0, v20, 36
	v_mul_f32_e32 v81, 0x3f317217, v80
	v_fma_f32 v81, v80, s62, -v81
	v_fmac_f32_e32 v82, s0, v70
	v_readlane_b32 s0, v21, 36
	v_fmac_f32_e32 v81, 0x3377d1cf, v80
	v_fmac_f32_e32 v81, 0x3f317217, v80
	v_fmac_f32_e32 v82, s0, v49
	v_readlane_b32 s0, v18, 37
	v_fmamk_f32 v78, v78, 0x3d800000, v77
	s_nop 0
	v_fmac_f32_e32 v82, s0, v68
	v_readlane_b32 s0, v19, 37
	s_nop 1
	v_fmac_f32_e32 v82, s0, v65
	v_readlane_b32 s0, v20, 37
	s_nop 1
	v_fmac_f32_e32 v82, s0, v69
	v_readlane_b32 s0, v21, 37
	s_nop 1
	v_fmac_f32_e32 v82, s0, v66
	v_readlane_b32 s0, v18, 38
	s_nop 1
	v_fmac_f32_e32 v82, s0, v67
	v_readlane_b32 s0, v19, 38
	s_nop 1
	v_fmac_f32_e32 v82, s0, v62
	v_readlane_b32 s0, v20, 38
	s_nop 1
	v_fmac_f32_e32 v82, s0, v61
	v_readlane_b32 s0, v21, 38
	s_nop 1
	v_fmac_f32_e32 v82, s0, v63
	v_readlane_b32 s0, v18, 39
	s_nop 1
	v_fmac_f32_e32 v82, s0, v58
	v_readlane_b32 s0, v19, 39
	s_nop 1
	v_fmac_f32_e32 v82, s0, v56
	v_readlane_b32 s0, v20, 39
	s_nop 1
	v_fmac_f32_e32 v82, s0, v57
	v_readlane_b32 s0, v21, 39
	s_nop 1
	v_fmac_f32_e32 v82, s0, v55
	v_mul_f32_e64 v83, |v82|, s60
	v_exp_f32_e32 v83, v83
	v_cmp_lt_f32_e64 s[0:1], |v80|, s63
	s_nop 1
	v_cndmask_b32_e64 v80, v80, v81, s[0:1]
	v_cndmask_b32_e32 v81, 0, v195, vcc
	v_sub_f32_e32 v80, v80, v81
	v_add_f32_e32 v81, 1.0, v83
	v_cmp_gt_f32_e32 vcc, s61, v81
	v_readlane_b32 s0, v18, 40
	v_sub_f32_e32 v79, v79, v80
	v_cndmask_b32_e64 v83, 0, 32, vcc
	v_ldexp_f32 v81, v81, v83
	v_fma_f32 v83, s0, v51, v53
	v_readlane_b32 s0, v19, 40
	v_log_f32_e32 v81, v81
	v_min_f32_e32 v80, 0, v82
	v_fmac_f32_e32 v83, s0, v50
	v_readlane_b32 s0, v20, 40
	v_mul_f32_e32 v82, 0x3f317217, v81
	v_fma_f32 v82, v81, s62, -v82
	v_fmac_f32_e32 v83, s0, v70
	v_readlane_b32 s0, v21, 40
	v_fmac_f32_e32 v82, 0x3377d1cf, v81
	v_fmac_f32_e32 v82, 0x3f317217, v81
	v_fmac_f32_e32 v83, s0, v49
	v_readlane_b32 s0, v18, 41
	v_fmamk_f32 v79, v79, 0x3d800000, v78
	s_nop 0
	v_fmac_f32_e32 v83, s0, v68
	v_readlane_b32 s0, v19, 41
	s_nop 1
	v_fmac_f32_e32 v83, s0, v65
	v_readlane_b32 s0, v20, 41
	s_nop 1
	v_fmac_f32_e32 v83, s0, v69
	v_readlane_b32 s0, v21, 41
	s_nop 1
	v_fmac_f32_e32 v83, s0, v66
	v_readlane_b32 s0, v18, 42
	s_nop 1
	v_fmac_f32_e32 v83, s0, v67
	v_readlane_b32 s0, v19, 42
	s_nop 1
	v_fmac_f32_e32 v83, s0, v62
	v_readlane_b32 s0, v20, 42
	s_nop 1
	v_fmac_f32_e32 v83, s0, v61
	v_readlane_b32 s0, v21, 42
	s_nop 1
	v_fmac_f32_e32 v83, s0, v63
	v_readlane_b32 s0, v18, 43
	s_nop 1
	v_fmac_f32_e32 v83, s0, v58
	v_readlane_b32 s0, v19, 43
	s_nop 1
	v_fmac_f32_e32 v83, s0, v56
	v_readlane_b32 s0, v20, 43
	s_nop 1
	v_fmac_f32_e32 v83, s0, v57
	v_readlane_b32 s0, v21, 43
	s_nop 1
	v_fmac_f32_e32 v83, s0, v55
	v_mul_f32_e64 v84, |v83|, s60
	v_exp_f32_e32 v84, v84
	v_cmp_lt_f32_e64 s[0:1], |v81|, s63
	s_nop 1
	v_cndmask_b32_e64 v81, v81, v82, s[0:1]
	v_cndmask_b32_e32 v82, 0, v195, vcc
	v_sub_f32_e32 v81, v81, v82
	v_add_f32_e32 v82, 1.0, v84
	v_cmp_gt_f32_e32 vcc, s61, v82
	v_readlane_b32 s0, v18, 44
	v_sub_f32_e32 v80, v80, v81
	v_cndmask_b32_e64 v84, 0, 32, vcc
	v_ldexp_f32 v82, v82, v84
	v_fma_f32 v84, s0, v51, v53
	v_readlane_b32 s0, v19, 44
	v_log_f32_e32 v82, v82
	v_min_f32_e32 v81, 0, v83
	v_fmac_f32_e32 v84, s0, v50
	v_readlane_b32 s0, v20, 44
	v_mul_f32_e32 v83, 0x3f317217, v82
	v_fma_f32 v83, v82, s62, -v83
	v_fmac_f32_e32 v84, s0, v70
	v_readlane_b32 s0, v21, 44
	v_fmac_f32_e32 v83, 0x3377d1cf, v82
	v_fmac_f32_e32 v83, 0x3f317217, v82
	v_fmac_f32_e32 v84, s0, v49
	v_readlane_b32 s0, v18, 45
	v_fmamk_f32 v80, v80, 0x3d800000, v79
	s_nop 0
	v_fmac_f32_e32 v84, s0, v68
	v_readlane_b32 s0, v19, 45
	s_nop 1
	v_fmac_f32_e32 v84, s0, v65
	v_readlane_b32 s0, v20, 45
	s_nop 1
	v_fmac_f32_e32 v84, s0, v69
	v_readlane_b32 s0, v21, 45
	s_nop 1
	v_fmac_f32_e32 v84, s0, v66
	v_readlane_b32 s0, v18, 46
	s_nop 1
	v_fmac_f32_e32 v84, s0, v67
	v_readlane_b32 s0, v19, 46
	s_nop 1
	v_fmac_f32_e32 v84, s0, v62
	v_readlane_b32 s0, v20, 46
	s_nop 1
	v_fmac_f32_e32 v84, s0, v61
	v_readlane_b32 s0, v21, 46
	s_nop 1
	v_fmac_f32_e32 v84, s0, v63
	v_readlane_b32 s0, v18, 47
	s_nop 1
	v_fmac_f32_e32 v84, s0, v58
	v_readlane_b32 s0, v19, 47
	s_nop 1
	v_fmac_f32_e32 v84, s0, v56
	v_readlane_b32 s0, v20, 47
	s_nop 1
	v_fmac_f32_e32 v84, s0, v57
	v_readlane_b32 s0, v21, 47
	s_nop 1
	v_fmac_f32_e32 v84, s0, v55
	v_mul_f32_e64 v85, |v84|, s60
	v_exp_f32_e32 v85, v85
	v_cmp_lt_f32_e64 s[0:1], |v82|, s63
	s_nop 1
	v_cndmask_b32_e64 v82, v82, v83, s[0:1]
	v_cndmask_b32_e32 v83, 0, v195, vcc
	v_sub_f32_e32 v82, v82, v83
	v_add_f32_e32 v83, 1.0, v85
	v_cmp_gt_f32_e32 vcc, s61, v83
	v_readlane_b32 s0, v18, 48
	v_sub_f32_e32 v81, v81, v82
	v_cndmask_b32_e64 v85, 0, 32, vcc
	v_ldexp_f32 v83, v83, v85
	v_fma_f32 v85, s0, v51, v53
	v_readlane_b32 s0, v19, 48
	v_log_f32_e32 v83, v83
	v_min_f32_e32 v82, 0, v84
	v_fmac_f32_e32 v85, s0, v50
	v_readlane_b32 s0, v20, 48
	v_mul_f32_e32 v84, 0x3f317217, v83
	v_fma_f32 v84, v83, s62, -v84
	v_fmac_f32_e32 v85, s0, v70
	v_readlane_b32 s0, v21, 48
	v_fmac_f32_e32 v84, 0x3377d1cf, v83
	v_fmac_f32_e32 v84, 0x3f317217, v83
	v_fmac_f32_e32 v85, s0, v49
	v_readlane_b32 s0, v18, 49
	v_fmamk_f32 v81, v81, 0x3d800000, v80
	s_nop 0
	v_fmac_f32_e32 v85, s0, v68
	v_readlane_b32 s0, v19, 49
	s_nop 1
	v_fmac_f32_e32 v85, s0, v65
	v_readlane_b32 s0, v20, 49
	s_nop 1
	v_fmac_f32_e32 v85, s0, v69
	v_readlane_b32 s0, v21, 49
	s_nop 1
	v_fmac_f32_e32 v85, s0, v66
	v_readlane_b32 s0, v18, 50
	s_nop 1
	v_fmac_f32_e32 v85, s0, v67
	v_readlane_b32 s0, v19, 50
	s_nop 1
	v_fmac_f32_e32 v85, s0, v62
	v_readlane_b32 s0, v20, 50
	s_nop 1
	v_fmac_f32_e32 v85, s0, v61
	v_readlane_b32 s0, v21, 50
	s_nop 1
	v_fmac_f32_e32 v85, s0, v63
	v_readlane_b32 s0, v18, 51
	s_nop 1
	v_fmac_f32_e32 v85, s0, v58
	v_readlane_b32 s0, v19, 51
	s_nop 1
	v_fmac_f32_e32 v85, s0, v56
	v_readlane_b32 s0, v20, 51
	s_nop 1
	v_fmac_f32_e32 v85, s0, v57
	v_readlane_b32 s0, v21, 51
	s_nop 1
	v_fmac_f32_e32 v85, s0, v55
	v_mul_f32_e64 v86, |v85|, s60
	v_exp_f32_e32 v86, v86
	v_cmp_lt_f32_e64 s[0:1], |v83|, s63
	s_nop 1
	v_cndmask_b32_e64 v83, v83, v84, s[0:1]
	v_cndmask_b32_e32 v84, 0, v195, vcc
	v_sub_f32_e32 v83, v83, v84
	v_add_f32_e32 v84, 1.0, v86
	v_cmp_gt_f32_e32 vcc, s61, v84
	v_readlane_b32 s0, v18, 52
	v_sub_f32_e32 v82, v82, v83
	v_cndmask_b32_e64 v86, 0, 32, vcc
	v_ldexp_f32 v84, v84, v86
	v_fma_f32 v86, s0, v51, v53
	v_readlane_b32 s0, v19, 52
	v_log_f32_e32 v84, v84
	v_min_f32_e32 v83, 0, v85
	v_fmac_f32_e32 v86, s0, v50
	v_readlane_b32 s0, v20, 52
	v_mul_f32_e32 v85, 0x3f317217, v84
	v_fma_f32 v85, v84, s62, -v85
	v_fmac_f32_e32 v86, s0, v70
	v_readlane_b32 s0, v21, 52
	v_fmac_f32_e32 v85, 0x3377d1cf, v84
	v_fmac_f32_e32 v85, 0x3f317217, v84
	v_fmac_f32_e32 v86, s0, v49
	v_readlane_b32 s0, v18, 53
	v_fmamk_f32 v82, v82, 0x3d800000, v81
	s_nop 0
	v_fmac_f32_e32 v86, s0, v68
	v_readlane_b32 s0, v19, 53
	s_nop 1
	v_fmac_f32_e32 v86, s0, v65
	v_readlane_b32 s0, v20, 53
	s_nop 1
	v_fmac_f32_e32 v86, s0, v69
	v_readlane_b32 s0, v21, 53
	s_nop 1
	v_fmac_f32_e32 v86, s0, v66
	v_readlane_b32 s0, v18, 54
	s_nop 1
	v_fmac_f32_e32 v86, s0, v67
	v_readlane_b32 s0, v19, 54
	s_nop 1
	v_fmac_f32_e32 v86, s0, v62
	v_readlane_b32 s0, v20, 54
	s_nop 1
	v_fmac_f32_e32 v86, s0, v61
	v_readlane_b32 s0, v21, 54
	s_nop 1
	v_fmac_f32_e32 v86, s0, v63
	v_readlane_b32 s0, v18, 55
	s_nop 1
	v_fmac_f32_e32 v86, s0, v58
	v_readlane_b32 s0, v19, 55
	s_nop 1
	v_fmac_f32_e32 v86, s0, v56
	v_readlane_b32 s0, v20, 55
	s_nop 1
	v_fmac_f32_e32 v86, s0, v57
	v_readlane_b32 s0, v21, 55
	s_nop 1
	v_fmac_f32_e32 v86, s0, v55
	v_mul_f32_e64 v87, |v86|, s60
	v_exp_f32_e32 v87, v87
	v_cmp_lt_f32_e64 s[0:1], |v84|, s63
	s_nop 1
	v_cndmask_b32_e64 v84, v84, v85, s[0:1]
	v_cndmask_b32_e32 v85, 0, v195, vcc
	v_sub_f32_e32 v84, v84, v85
	v_add_f32_e32 v85, 1.0, v87
	v_cmp_gt_f32_e32 vcc, s61, v85
	v_readlane_b32 s0, v18, 56
	v_sub_f32_e32 v83, v83, v84
	v_cndmask_b32_e64 v87, 0, 32, vcc
	v_ldexp_f32 v85, v85, v87
	v_fma_f32 v87, s0, v51, v53
	v_readlane_b32 s0, v19, 56
	v_log_f32_e32 v85, v85
	v_min_f32_e32 v84, 0, v86
	v_fmac_f32_e32 v87, s0, v50
	v_readlane_b32 s0, v20, 56
	v_mul_f32_e32 v86, 0x3f317217, v85
	v_fma_f32 v86, v85, s62, -v86
	v_fmac_f32_e32 v87, s0, v70
	v_readlane_b32 s0, v21, 56
	v_fmac_f32_e32 v86, 0x3377d1cf, v85
	v_fmac_f32_e32 v86, 0x3f317217, v85
	v_fmac_f32_e32 v87, s0, v49
	v_readlane_b32 s0, v18, 57
	v_fmamk_f32 v83, v83, 0x3d800000, v82
	s_nop 0
	v_fmac_f32_e32 v87, s0, v68
	v_readlane_b32 s0, v19, 57
	s_nop 1
	v_fmac_f32_e32 v87, s0, v65
	v_readlane_b32 s0, v20, 57
	s_nop 1
	v_fmac_f32_e32 v87, s0, v69
	v_readlane_b32 s0, v21, 57
	s_nop 1
	v_fmac_f32_e32 v87, s0, v66
	v_readlane_b32 s0, v18, 58
	s_nop 1
	v_fmac_f32_e32 v87, s0, v67
	v_readlane_b32 s0, v19, 58
	s_nop 1
	v_fmac_f32_e32 v87, s0, v62
	v_readlane_b32 s0, v20, 58
	s_nop 1
	v_fmac_f32_e32 v87, s0, v61
	v_readlane_b32 s0, v21, 58
	s_nop 1
	v_fmac_f32_e32 v87, s0, v63
	v_readlane_b32 s0, v18, 59
	s_nop 1
	v_fmac_f32_e32 v87, s0, v58
	v_readlane_b32 s0, v19, 59
	s_nop 1
	v_fmac_f32_e32 v87, s0, v56
	v_readlane_b32 s0, v20, 59
	s_nop 1
	v_fmac_f32_e32 v87, s0, v57
	v_readlane_b32 s0, v21, 59
	s_nop 1
	v_fmac_f32_e32 v87, s0, v55
	v_cmp_lt_f32_e64 s[0:1], |v85|, s63
	v_mul_f32_e64 v88, |v87|, s60
	v_exp_f32_e32 v88, v88
	v_cndmask_b32_e64 v85, v85, v86, s[0:1]
	v_readlane_b32 s0, v18, 60
	v_cndmask_b32_e32 v86, 0, v195, vcc
	v_sub_f32_e32 v85, v85, v86
	v_fmac_f32_e32 v53, s0, v51
	v_readlane_b32 s0, v19, 60
	v_add_f32_e32 v86, 1.0, v88
	v_cmp_gt_f32_e32 vcc, s61, v86
	v_fmac_f32_e32 v53, s0, v50
	v_readlane_b32 s0, v20, 60
	v_cndmask_b32_e64 v88, 0, 32, vcc
	v_ldexp_f32 v86, v86, v88
	v_fmac_f32_e32 v53, s0, v70
	v_readlane_b32 s0, v21, 60
	v_log_f32_e32 v86, v86
	v_sub_f32_e32 v84, v84, v85
	v_fmac_f32_e32 v53, s0, v49
	v_readlane_b32 s0, v18, 61
	v_min_f32_e32 v85, 0, v87
	v_mul_f32_e32 v87, 0x3f317217, v86
	v_fmac_f32_e32 v53, s0, v68
	v_readlane_b32 s0, v19, 61
	v_fma_f32 v87, v86, s62, -v87
	v_fmac_f32_e32 v87, 0x3377d1cf, v86
	v_fmac_f32_e32 v53, s0, v65
	v_readlane_b32 s0, v20, 61
	v_fmac_f32_e32 v87, 0x3f317217, v86
	v_fmamk_f32 v84, v84, 0x3d800000, v83
	v_fmac_f32_e32 v53, s0, v69
	v_readlane_b32 s0, v21, 61
	s_nop 1
	v_fmac_f32_e32 v53, s0, v66
	v_readlane_b32 s0, v18, 62
	s_nop 1
	v_fmac_f32_e32 v53, s0, v67
	v_readlane_b32 s0, v19, 62
	s_nop 1
	v_fmac_f32_e32 v53, s0, v62
	v_readlane_b32 s0, v20, 62
	s_nop 1
	v_fmac_f32_e32 v53, s0, v61
	v_readlane_b32 s0, v21, 62
	s_nop 1
	v_fmac_f32_e32 v53, s0, v63
	v_readlane_b32 s0, v18, 63
	s_nop 1
	v_fmac_f32_e32 v53, s0, v58
	v_readlane_b32 s0, v19, 63
	v_lshlrev_b32_e32 v58, 16, v64
	s_nop 0
	v_fmac_f32_e32 v53, s0, v56
	v_readlane_b32 s0, v20, 63
	v_cndmask_b32_e32 v20, 0, v195, vcc
	s_nop 0
	v_fmac_f32_e32 v53, s0, v57
	v_readlane_b32 s0, v21, 63
	s_nop 1
	v_fmac_f32_e32 v53, s0, v55
	v_mul_f32_e64 v18, |v53|, s60
	v_exp_f32_e32 v18, v18
	v_cmp_lt_f32_e64 s[0:1], |v86|, s63
	v_add_f32_e32 v18, 1.0, v18
	s_nop 0
	v_cndmask_b32_e64 v19, v86, v87, s[0:1]
	v_cmp_gt_f32_e32 vcc, s61, v18
	v_sub_f32_e32 v19, v19, v20
	v_sub_f32_e32 v19, v85, v19
	v_cndmask_b32_e64 v20, 0, 32, vcc
	v_ldexp_f32 v18, v18, v20
	v_log_f32_e32 v18, v18
	v_fmamk_f32 v55, v19, 0x3d800000, v84
	v_min_f32_e32 v19, 0, v53
	v_mul_f32_e32 v20, 0x3f317217, v18
	v_fma_f32 v20, v18, s62, -v20
	v_fmac_f32_e32 v20, 0x3377d1cf, v18
	v_fmac_f32_e32 v20, 0x3f317217, v18
	v_cmp_lt_f32_e64 s[0:1], |v18|, s63
	s_nop 1
	v_cndmask_b32_e64 v18, v18, v20, s[0:1]
	v_cndmask_b32_e32 v20, 0, v195, vcc
	v_sub_f32_e32 v18, v18, v20
	v_sub_f32_e32 v18, v19, v18
	v_fmamk_f32 v53, v18, 0x3d800000, v55
	ds_write_b32 v141, v53
	s_waitcnt lgkmcnt(0)
	s_barrier
	ds_read2st64_b32 v[18:19], v143 offset1:2
	ds_read2st64_b32 v[50:51], v143 offset0:4 offset1:6
	v_or_b32_e32 v20, s21, v149
	s_waitcnt lgkmcnt(1)
	v_add_f32_e32 v49, 0, v18
	v_add_f32_e32 v21, v49, v19
	s_waitcnt lgkmcnt(0)
	v_add_f32_e32 v18, v21, v50
	v_add_f32_e32 v19, v18, v51
	v_mov_b64_e32 v[50:51], s[26:27]
	v_mad_i64_i32 v[174:175], s[0:1], v20, s53, v[50:51]
	s_lshr_b32 s0, s69, 1
	v_lshl_add_u64 v[50:51], s[24:25], 1, v[174:175]
	s_and_b32 s70, s0, 0x7fffff80
	v_lshl_add_u64 v[50:51], v[50:51], 0, v[156:157]
	s_lshl_b32 s0, s70, 1
	s_mov_b32 s1, s25
	v_lshl_add_u64 v[50:51], v[50:51], 0, s[0:1]
	v_lshl_add_u64 v[56:57], v[50:51], 0, s[30:31]
	v_add_co_u32_e32 v50, vcc, s54, v50
	s_nop 1
	v_addc_co_u32_e32 v51, vcc, 0, v51, vcc
	v_cmp_eq_u32_e32 vcc, 1, v1
	s_mul_hi_u32 s99, s67, 0xaaaaaaab
	v_and_b32_e32 v86, 15, v0
	v_bfe_u32 v87, v0, 4, 2
	v_lshrrev_b32_e32 v88, 6, v0
	s_lshr_b32 s99, s99, 3
	s_mul_i32 s100, s99, 12
	s_sub_u32 s100, s67, s100
	s_lshl_b32 s101, s99, 2
	s_add_i32 s101, s101, s100
	s_add_i32 s101, s101, -8
	s_lshl_b32 s101, s101, 16
	s_add_u32 s0, s44, s101
	s_addc_u32 s1, s45, 0
	v_lshrrev_b32_e32 v89, 2, v86
	v_and_b32_e32 v90, 3, v86
	v_lshl_add_u32 v89, v89, 3, v90
	v_lshlrev_b32_e32 v89, 8, v89
	v_lshl_add_u32 v89, v87, 4, v89
	v_lshl_add_u32 v89, v88, 13, v89
	global_load_dwordx4 v[208:211], v89, s[0:1]
	global_load_dwordx4 v[212:215], v89, s[0:1] offset:64
	global_load_dwordx4 v[216:219], v89, s[0:1] offset:128
	global_load_dwordx4 v[220:223], v89, s[0:1] offset:192
	global_load_dwordx4 v[224:227], v89, s[0:1] offset:1024
	global_load_dwordx4 v[228:231], v89, s[0:1] offset:1088
	global_load_dwordx4 v[232:235], v89, s[0:1] offset:1152
	global_load_dwordx4 v[236:239], v89, s[0:1] offset:1216
	s_mul_i32 s99, s99, 0xe8000
	s_lshl_b32 s101, s100, 9
	s_add_i32 s99, s99, s101
	s_addk_i32 s99, 6144
	v_mul_u32_u24_e32 v92, 0x3a00, v86
	v_lshl_add_u32 v92, v87, 4, v92
	v_lshl_add_u32 v92, v88, 6, v92
	v_add_u32_e32 v92, s99, v92
	v_mov_b32_e32 v93, 0
	s_mov_b64 s[98:99], 0x3a000
	v_lshl_add_u64 v[120:121], v[92:93], 0, s[26:27]
	v_lshl_add_u64 v[122:123], v[120:121], 0, s[98:99]
	v_lshl_add_u64 v[124:125], v[122:123], 0, s[98:99]
	v_lshl_add_u64 v[126:127], v[124:125], 0, s[98:99]
	global_load_dwordx4 v[96:99], v[120:121], off offset:-2048
	global_load_dwordx4 v[100:103], v[122:123], off offset:-2048
	global_load_dwordx4 v[104:107], v[124:125], off offset:-2048
	global_load_dwordx4 v[108:111], v[126:127], off offset:-2048
	v_readlane_b32 s98, v255, 25
	v_readlane_b32 s99, v255, 26
	s_lshl_b32 s101, s100, 10
	s_addk_i32 s101, 0xe000
	v_lshl_add_u32 v94, v87, 5, s101
	v_lshl_add_u32 v94, v88, 7, v94
	s_nop 3
	global_load_dwordx4 v[112:115], v94, s[98:99]
	global_load_dwordx4 v[116:119], v94, s[98:99] offset:16
	v_cndmask_b32_e32 v20, 0, v49, vcc
	v_cmp_eq_u32_e32 vcc, 2, v1
	v_mul_f32_e32 v51, 0x3fb8aa3b, v72
	v_exp_f32_e32 v51, v51
	v_cndmask_b32_e32 v20, v20, v21, vcc
	v_cmp_eq_u32_e32 vcc, 3, v1
	v_mul_f32_e32 v29, v29, v51
	s_nop 0
	v_cndmask_b32_e32 v20, v20, v18, vcc
	v_cmp_eq_u32_e32 vcc, 4, v1
	v_mul_f32_e32 v51, 0x3fb8aa3b, v73
	v_exp_f32_e32 v51, v51
	v_cndmask_b32_e32 v19, v20, v19, vcc
	v_mul_f32_e32 v20, 0x3fb8aa3b, v71
	v_exp_f32_e32 v20, v20
	v_mul_f32_e32 v50, 0x3fb8aa3b, v19
	v_exp_f32_e32 v50, v50
	v_mul_f32_e32 v28, v28, v51
	v_mul_f32_e32 v20, v30, v20
	v_cvt_pk_bf16_f32 v30, v20, s0
	ds_write_b16 v191, v30 offset:2560
	v_mul_f32_e32 v30, 0xbfb8aa3b, v71
	v_exp_f32_e32 v30, v30
	v_mul_f32_e32 v20, v20, v50
	v_cvt_pk_bf16_f32 v20, v20, s0
	ds_write_b16 v191, v20 offset:19968
	v_mul_f32_e32 v20, v30, v54
	v_cvt_pk_bf16_f32 v30, v29, s0
	ds_write_b16 v191, v30 offset:2832
	v_mul_f32_e32 v30, 0xbfb8aa3b, v72
	v_exp_f32_e32 v30, v30
	v_mul_f32_e32 v29, v29, v50
	v_cvt_pk_bf16_f32 v29, v29, s0
	ds_write_b16 v191, v29 offset:20240
	v_mul_f32_e32 v29, v30, v52
	v_cvt_pk_bf16_f32 v30, v28, s0
	v_mul_f32_e32 v51, 0x3fb8aa3b, v74
	ds_write_b16 v191, v30 offset:3104
	v_mul_f32_e32 v30, 0xbfb8aa3b, v73
	v_exp_f32_e32 v51, v51
	v_exp_f32_e32 v30, v30
	v_mul_f32_e32 v28, v28, v50
	v_cvt_pk_bf16_f32 v28, v28, s0
	v_mul_f32_e32 v27, v27, v51
	ds_write_b16 v191, v28 offset:20512
	v_mul_f32_e32 v28, v30, v48
	v_cvt_pk_bf16_f32 v30, v27, s0
	v_mul_f32_e32 v48, 0x3fb8aa3b, v75
	ds_write_b16 v191, v30 offset:3376
	v_mul_f32_e32 v30, 0xbfb8aa3b, v74
	v_exp_f32_e32 v48, v48
	v_exp_f32_e32 v30, v30
	v_mul_f32_e32 v27, v27, v50
	v_cvt_pk_bf16_f32 v27, v27, s0
	v_mul_f32_e32 v25, v25, v48
	ds_write_b16 v191, v27 offset:20784
	v_mul_f32_e32 v27, v30, v47
	v_cvt_pk_bf16_f32 v30, v25, s0
	v_mul_f32_e32 v47, 0x3fb8aa3b, v76
	ds_write_b16 v191, v30 offset:3648
	v_mul_f32_e32 v30, 0xbfb8aa3b, v75
	v_exp_f32_e32 v47, v47
	v_exp_f32_e32 v30, v30
	v_mul_f32_e32 v25, v25, v50
	v_cvt_pk_bf16_f32 v25, v25, s0
	v_mul_f32_e32 v24, v24, v47
	ds_write_b16 v191, v25 offset:21056
	v_mul_f32_e32 v25, v30, v45
	v_cvt_pk_bf16_f32 v30, v24, s0
	v_mul_f32_e32 v45, 0x3fb8aa3b, v77
	ds_write_b16 v191, v30 offset:3920
	v_mul_f32_e32 v30, 0xbfb8aa3b, v76
	v_exp_f32_e32 v45, v45
	v_exp_f32_e32 v30, v30
	v_mul_f32_e32 v24, v24, v50
	v_cvt_pk_bf16_f32 v24, v24, s0
	v_mul_f32_e32 v23, v23, v45
	ds_write_b16 v191, v24 offset:21328
	v_mul_f32_e32 v24, v30, v43
	v_cvt_pk_bf16_f32 v30, v23, s0
	v_mul_f32_e32 v43, 0x3fb8aa3b, v78
	ds_write_b16 v191, v30 offset:4192
	v_mul_f32_e32 v30, 0xbfb8aa3b, v77
	v_exp_f32_e32 v43, v43
	v_exp_f32_e32 v30, v30
	v_mul_f32_e32 v23, v23, v50
	v_cvt_pk_bf16_f32 v23, v23, s0
	v_mul_f32_e32 v22, v22, v43
	ds_write_b16 v191, v23 offset:21600
	v_mul_f32_e32 v23, v30, v41
	v_cvt_pk_bf16_f32 v30, v22, s0
	v_mul_f32_e32 v41, 0x3fb8aa3b, v79
	ds_write_b16 v191, v30 offset:4464
	v_mul_f32_e32 v30, 0xbfb8aa3b, v78
	v_exp_f32_e32 v41, v41
	v_exp_f32_e32 v30, v30
	v_mul_f32_e32 v22, v22, v50
	v_cvt_pk_bf16_f32 v22, v22, s0
	v_mul_f32_e32 v26, v26, v41
	ds_write_b16 v191, v22 offset:21872
	v_mul_f32_e32 v22, v30, v39
	v_cvt_pk_bf16_f32 v30, v26, s0
	ds_write_b16 v191, v30 offset:4736
	v_mul_f32_e32 v30, 0xbfb8aa3b, v79
	v_exp_f32_e32 v30, v30
	v_mul_f32_e32 v39, 0x3fb8aa3b, v80
	v_exp_f32_e32 v39, v39
	v_mul_f32_e32 v26, v26, v50
	v_cvt_pk_bf16_f32 v26, v26, s0
	ds_write_b16 v191, v26 offset:22144
	v_mul_f32_e32 v26, v30, v46
	v_mul_f32_e32 v30, 0x3db504f3, v37
	v_mul_f32_e32 v30, v30, v39
	v_cvt_pk_bf16_f32 v37, v30, s0
	v_mul_f32_e32 v39, 0x3fb8aa3b, v81
	ds_write_b16 v191, v37 offset:5008
	v_mul_f32_e32 v37, 0xbfb8aa3b, v80
	v_exp_f32_e32 v39, v39
	v_exp_f32_e32 v37, v37
	v_mul_f32_e32 v30, v30, v50
	v_cvt_pk_bf16_f32 v30, v30, s0
	v_mul_f32_e32 v36, v36, v39
	ds_write_b16 v191, v30 offset:22416
	v_mul_f32_e32 v30, v37, v44
	v_cvt_pk_bf16_f32 v37, v36, s0
	v_mul_f32_e32 v39, 0x3fb8aa3b, v82
	ds_write_b16 v191, v37 offset:5280
	v_mul_f32_e32 v37, 0xbfb8aa3b, v81
	v_exp_f32_e32 v39, v39
	v_exp_f32_e32 v37, v37
	v_mul_f32_e32 v36, v36, v50
	v_cvt_pk_bf16_f32 v36, v36, s0
	v_mul_f32_e32 v35, v35, v39
	ds_write_b16 v191, v36 offset:22688
	v_mul_f32_e32 v36, v37, v42
	v_cvt_pk_bf16_f32 v37, v35, s0
	v_mul_f32_e32 v39, 0x3fb8aa3b, v83
	ds_write_b16 v191, v37 offset:5552
	v_mul_f32_e32 v37, 0xbfb8aa3b, v82
	v_exp_f32_e32 v39, v39
	v_exp_f32_e32 v37, v37
	v_mul_f32_e32 v35, v35, v50
	v_cvt_pk_bf16_f32 v35, v35, s0
	v_mul_f32_e32 v34, v34, v39
	ds_write_b16 v191, v35 offset:22960
	v_mul_f32_e32 v35, v37, v40
	v_cvt_pk_bf16_f32 v37, v34, s0
	v_mul_f32_e32 v39, 0x3fb8aa3b, v84
	ds_write_b16 v191, v37 offset:5824
	v_mul_f32_e32 v37, 0xbfb8aa3b, v83
	v_exp_f32_e32 v39, v39
	v_exp_f32_e32 v37, v37
	v_mul_f32_e32 v34, v34, v50
	v_cvt_pk_bf16_f32 v34, v34, s0
	v_mul_f32_e32 v33, v33, v39
	ds_write_b16 v191, v34 offset:23232
	v_mul_f32_e32 v34, v37, v38
	v_cvt_pk_bf16_f32 v37, v33, s0
	v_mul_f32_e32 v38, 0x3fb8aa3b, v55
	ds_write_b16 v191, v37 offset:6096
	v_mul_f32_e32 v37, 0xbfb8aa3b, v84
	v_exp_f32_e32 v38, v38
	v_exp_f32_e32 v37, v37
	v_mul_f32_e32 v33, v33, v50
	v_cvt_pk_bf16_f32 v33, v33, s0
	v_mul_f32_e32 v32, v32, v38
	ds_write_b16 v191, v33 offset:23504
	v_mul_f32_e32 v33, v37, v58
	v_cvt_pk_bf16_f32 v37, v32, s0
	v_mul_f32_e32 v38, 0x3fb8aa3b, v53
	ds_write_b16 v191, v37 offset:6368
	v_mul_f32_e32 v37, 0xbfb8aa3b, v55
	v_exp_f32_e32 v38, v38
	v_exp_f32_e32 v37, v37
	v_mul_f32_e32 v32, v32, v50
	v_cvt_pk_bf16_f32 v32, v32, s0
	v_mul_f32_e32 v31, v31, v38
	ds_write_b16 v191, v32 offset:23776
	v_mul_f32_e32 v32, v37, v59
	v_cvt_pk_bf16_f32 v37, v31, s0
	ds_write_b16 v191, v37 offset:6640
	v_mul_f32_e32 v37, 0xbfb8aa3b, v53
	v_exp_f32_e32 v37, v37
	v_mul_f32_e32 v31, v50, v31
	v_cvt_pk_bf16_f32 v31, v31, s0
	ds_write_b16 v191, v31 offset:24048
	v_mul_f32_e32 v31, v37, v60
	s_and_saveexec_b64 s[0:1], s[2:3]
	s_cbranch_execnz .LBB0_1394
	s_or_b64 exec, exec, s[0:1]
	s_and_saveexec_b64 s[0:1], s[4:5]
	s_cbranch_execnz .LBB0_1395

.LBB0_1362:
	v_mad_u32_u24 v136, v149, s43, v142
	s_waitcnt lgkmcnt(0)
	s_barrier
	v_and_b32_e32 v128, 15, v0
	v_bfe_u32 v129, v0, 4, 2
	v_lshrrev_b32_e32 v130, 6, v0
	v_mul_u32_u24_e32 v131, 0x110, v128
	v_lshl_add_u32 v131, v129, 4, v131
	v_mul_u32_u24_e32 v132, 0x90, v128
	v_lshl_add_u32 v132, v129, 4, v132
	v_mul_u32_u24_e32 v133, 4608, v130
	v_lshrrev_b32_e32 v82, 2, v128
	v_and_b32_e32 v83, 3, v128
	v_lshl_add_u32 v82, v82, 3, v83
	v_mul_u32_u24_e32 v82, 0x90, v82
	v_lshl_add_u32 v82, v129, 4, v82
	v_add_u32_e32 v133, v133, v82
	v_add_u32_e32 v133, 0x16000, v133
	v_add_u32_e32 v132, 0x13c00, v132
	v_lshlrev_b32_e32 v83, 5, v128
	v_lshl_add_u32 v82, v130, 2, v83
	v_mov_b32_e32 v84, 0x358637bd
	s_waitcnt vmcnt(0)
	ds_read_b128 v[34:37], v133
	ds_read_b128 v[38:41], v133 offset:576
	ds_read_b128 v[42:45], v133 offset:64
	ds_read_b128 v[46:49], v133 offset:640
	ds_read_b128 v[50:53], v131 offset:19968
	ds_read_b128 v[54:57], v131 offset:20032
	ds_read_b128 v[58:61], v131 offset:20096
	ds_read_b128 v[62:65], v131 offset:20160
	ds_read_b128 v[160:163], v132
	ds_read_b128 v[66:69], v131 offset:24320
	ds_read_b128 v[70:73], v131 offset:24384
	ds_read_b128 v[74:77], v131 offset:24448
	ds_read_b128 v[78:81], v131 offset:24512
	ds_read_b128 v[168:171], v132 offset:2304
	s_waitcnt lgkmcnt(5)
	v_mfma_f32_16x16x32_bf16 v[2:5], v[208:211], v[50:53], 0
	v_mfma_f32_16x16x32_bf16 v[6:9], v[224:227], v[50:53], 0
	v_mfma_f32_16x16x32_bf16 v[2:5], v[212:215], v[54:57], v[2:5]
	v_mfma_f32_16x16x32_bf16 v[6:9], v[228:231], v[54:57], v[6:9]
	v_mfma_f32_16x16x32_bf16 v[2:5], v[216:219], v[58:61], v[2:5]
	v_mfma_f32_16x16x32_bf16 v[6:9], v[232:235], v[58:61], v[6:9]
	v_mfma_f32_16x16x32_bf16 v[2:5], v[220:223], v[62:65], v[2:5]
	v_mfma_f32_16x16x32_bf16 v[6:9], v[236:239], v[62:65], v[6:9]
	v_mfma_f32_16x16x32_bf16 v[2:5], v[34:37], v[160:163], v[2:5]
	v_mfma_f32_16x16x32_bf16 v[6:9], v[38:41], v[160:163], v[6:9]
	ds_read_b128 v[50:53], v131 offset:28672
	ds_read_b128 v[54:57], v131 offset:28736
	ds_read_b128 v[58:61], v131 offset:28800
	ds_read_b128 v[62:65], v131 offset:28864
	ds_read_b128 v[160:163], v132 offset:4608
	ds_read_b128 v[164:167], v132 offset:4672
	s_waitcnt lgkmcnt(6)
	v_mfma_f32_16x16x32_bf16 v[10:13], v[208:211], v[66:69], 0
	v_mfma_f32_16x16x32_bf16 v[14:17], v[224:227], v[66:69], 0
	v_mfma_f32_16x16x32_bf16 v[10:13], v[212:215], v[70:73], v[10:13]
	v_mfma_f32_16x16x32_bf16 v[14:17], v[228:231], v[70:73], v[14:17]
	v_mfma_f32_16x16x32_bf16 v[10:13], v[216:219], v[74:77], v[10:13]
	v_mfma_f32_16x16x32_bf16 v[14:17], v[232:235], v[74:77], v[14:17]
	v_mfma_f32_16x16x32_bf16 v[10:13], v[220:223], v[78:81], v[10:13]
	v_mfma_f32_16x16x32_bf16 v[14:17], v[236:239], v[78:81], v[14:17]
	v_mfma_f32_16x16x32_bf16 v[10:13], v[34:37], v[168:171], v[10:13]
	v_mfma_f32_16x16x32_bf16 v[14:17], v[38:41], v[168:171], v[14:17]
	ds_read_b128 v[66:69], v131 offset:33024
	ds_read_b128 v[70:73], v131 offset:33088
	ds_read_b128 v[74:77], v131 offset:33152
	ds_read_b128 v[78:81], v131 offset:33216
	ds_read_b128 v[168:171], v132 offset:6912
	ds_read_b128 v[172:175], v132 offset:6976
	s_waitcnt lgkmcnt(6)
	v_mfma_f32_16x16x32_bf16 v[18:21], v[208:211], v[50:53], 0
	v_mfma_f32_16x16x32_bf16 v[22:25], v[224:227], v[50:53], 0
	v_mfma_f32_16x16x32_bf16 v[18:21], v[212:215], v[54:57], v[18:21]
	v_mfma_f32_16x16x32_bf16 v[22:25], v[228:231], v[54:57], v[22:25]
	v_mfma_f32_16x16x32_bf16 v[18:21], v[216:219], v[58:61], v[18:21]
	v_mfma_f32_16x16x32_bf16 v[22:25], v[232:235], v[58:61], v[22:25]
	v_mfma_f32_16x16x32_bf16 v[18:21], v[220:223], v[62:65], v[18:21]
	v_mfma_f32_16x16x32_bf16 v[22:25], v[236:239], v[62:65], v[22:25]
	v_mfma_f32_16x16x32_bf16 v[18:21], v[34:37], v[160:163], v[18:21]
	v_mfma_f32_16x16x32_bf16 v[22:25], v[38:41], v[160:163], v[22:25]
	v_mfma_f32_16x16x32_bf16 v[18:21], v[42:45], v[164:167], v[18:21]
	v_mfma_f32_16x16x32_bf16 v[22:25], v[46:49], v[164:167], v[22:25]
	s_waitcnt lgkmcnt(0)
	v_mfma_f32_16x16x32_bf16 v[26:29], v[208:211], v[66:69], 0
	v_mfma_f32_16x16x32_bf16 v[30:33], v[224:227], v[66:69], 0
	v_mfma_f32_16x16x32_bf16 v[26:29], v[212:215], v[70:73], v[26:29]
	v_mfma_f32_16x16x32_bf16 v[30:33], v[228:231], v[70:73], v[30:33]
	v_mfma_f32_16x16x32_bf16 v[26:29], v[216:219], v[74:77], v[26:29]
	v_mfma_f32_16x16x32_bf16 v[30:33], v[232:235], v[74:77], v[30:33]
	v_mfma_f32_16x16x32_bf16 v[26:29], v[220:223], v[78:81], v[26:29]
	v_mfma_f32_16x16x32_bf16 v[30:33], v[236:239], v[78:81], v[30:33]
	v_mfma_f32_16x16x32_bf16 v[26:29], v[34:37], v[168:171], v[26:29]
	v_mfma_f32_16x16x32_bf16 v[30:33], v[38:41], v[168:171], v[30:33]
	v_mfma_f32_16x16x32_bf16 v[26:29], v[42:45], v[172:175], v[26:29]
	v_mfma_f32_16x16x32_bf16 v[30:33], v[46:49], v[172:175], v[30:33]
	s_nop 7
	s_nop 1
	v_mul_f32_e32 v176, v2, v2
	v_fmac_f32_e32 v176, v3, v3
	v_fmac_f32_e32 v176, v4, v4
	v_fmac_f32_e32 v176, v5, v5
	v_fmac_f32_e32 v176, v6, v6
	v_fmac_f32_e32 v176, v7, v7
	v_fmac_f32_e32 v176, v8, v8
	v_fmac_f32_e32 v176, v9, v9
	v_mul_f32_e32 v177, v10, v10
	v_fmac_f32_e32 v177, v11, v11
	v_fmac_f32_e32 v177, v12, v12
	v_fmac_f32_e32 v177, v13, v13
	v_fmac_f32_e32 v177, v14, v14
	v_fmac_f32_e32 v177, v15, v15
	v_fmac_f32_e32 v177, v16, v16
	v_fmac_f32_e32 v177, v17, v17
	v_mul_f32_e32 v86, v18, v18
	v_fmac_f32_e32 v86, v19, v19
	v_fmac_f32_e32 v86, v20, v20
	v_fmac_f32_e32 v86, v21, v21
	v_fmac_f32_e32 v86, v22, v22
	v_fmac_f32_e32 v86, v23, v23
	v_fmac_f32_e32 v86, v24, v24
	v_fmac_f32_e32 v86, v25, v25
	v_mul_f32_e32 v87, v26, v26
	v_fmac_f32_e32 v87, v27, v27
	v_fmac_f32_e32 v87, v28, v28
	v_fmac_f32_e32 v87, v29, v29
	v_fmac_f32_e32 v87, v30, v30
	v_fmac_f32_e32 v87, v31, v31
	v_fmac_f32_e32 v87, v32, v32
	v_fmac_f32_e32 v87, v33, v33
	ds_swizzle_b32 v88, v176 offset:0x401F
	ds_swizzle_b32 v89, v177 offset:0x401F
	ds_swizzle_b32 v90, v86 offset:0x401F
	ds_swizzle_b32 v91, v87 offset:0x401F
	s_waitcnt lgkmcnt(0)
	v_add_f32_e32 v176, v176, v88
	v_add_f32_e32 v177, v177, v89
	v_add_f32_e32 v86, v86, v90
	v_add_f32_e32 v87, v87, v91
	v_mov_b32_e32 v88, v176
	v_mov_b32_e32 v89, v177
	v_mov_b32_e32 v90, v86
	v_mov_b32_e32 v91, v87
	s_nop 1
	v_permlane32_swap_b32_e32 v88, v176
	v_permlane32_swap_b32_e32 v89, v177
	v_permlane32_swap_b32_e32 v90, v86
	v_permlane32_swap_b32_e32 v91, v87
	s_nop 1
	v_add_f32_e32 v176, v176, v88
	v_add_f32_e32 v177, v177, v89
	v_add_f32_e32 v86, v86, v90
	v_add_f32_e32 v87, v87, v91
	ds_write_b32 v82, v176
	ds_write_b32 v82, v177 offset:512
	ds_write_b32 v82, v86 offset:1024
	ds_write_b32 v82, v87 offset:1536
	s_waitcnt lgkmcnt(0)
	s_barrier
	ds_read_b128 v[50:53], v83
	ds_read_b128 v[54:57], v83 offset:16
	ds_read_b128 v[58:61], v83 offset:512
	ds_read_b128 v[62:65], v83 offset:528
	ds_read_b128 v[66:69], v83 offset:1024
	ds_read_b128 v[70:73], v83 offset:1040
	ds_read_b128 v[74:77], v83 offset:1536
	ds_read_b128 v[78:81], v83 offset:1552
	s_waitcnt lgkmcnt(0)
	s_barrier
	v_add_f32_e32 v50, v50, v51
	v_add_f32_e32 v52, v52, v53
	v_add_f32_e32 v54, v54, v55
	v_add_f32_e32 v56, v56, v57
	v_add_f32_e32 v50, v50, v52
	v_add_f32_e32 v54, v54, v56
	v_add_f32_e32 v50, v50, v54
	v_fmamk_f32 v50, v50, 0x3b800000, v84
	v_rsq_f32_e32 v176, v50
	v_add_f32_e32 v58, v58, v59
	v_add_f32_e32 v60, v60, v61
	v_add_f32_e32 v62, v62, v63
	v_add_f32_e32 v64, v64, v65
	v_add_f32_e32 v58, v58, v60
	v_add_f32_e32 v62, v62, v64
	v_add_f32_e32 v58, v58, v62
	v_fmamk_f32 v58, v58, 0x3b800000, v84
	v_rsq_f32_e32 v177, v58
	v_add_f32_e32 v66, v66, v67
	v_add_f32_e32 v68, v68, v69
	v_add_f32_e32 v70, v70, v71
	v_add_f32_e32 v72, v72, v73
	v_add_f32_e32 v66, v66, v68
	v_add_f32_e32 v70, v70, v72
	v_add_f32_e32 v66, v66, v70
	v_fmamk_f32 v66, v66, 0x3b800000, v84
	v_rsq_f32_e32 v86, v66
	v_add_f32_e32 v74, v74, v75
	v_add_f32_e32 v76, v76, v77
	v_add_f32_e32 v78, v78, v79
	v_add_f32_e32 v80, v80, v81
	v_add_f32_e32 v74, v74, v76
	v_add_f32_e32 v78, v78, v80
	v_add_f32_e32 v74, v74, v78
	v_fmamk_f32 v74, v74, 0x3b800000, v84
	v_rsq_f32_e32 v87, v74
	v_lshlrev_b32_e32 v66, 16, v96
	v_and_b32_e32 v67, 0xffff0000, v96
	v_lshlrev_b32_e32 v68, 16, v97
	v_and_b32_e32 v69, 0xffff0000, v97
	v_mul_f32_e32 v2, v2, v176
	v_mul_f32_e32 v3, v3, v176
	v_mul_f32_e32 v4, v4, v176
	v_mul_f32_e32 v5, v5, v176
	v_mul_f32_e32 v2, v2, v112
	v_mul_f32_e32 v3, v3, v113
	v_mul_f32_e32 v4, v4, v114
	v_mul_f32_e32 v5, v5, v115
	v_mul_f32_e32 v2, v2, v66
	v_mul_f32_e32 v3, v3, v67
	v_mul_f32_e32 v4, v4, v68
	v_mul_f32_e32 v5, v5, v69
	v_lshlrev_b32_e32 v66, 16, v98
	v_and_b32_e32 v67, 0xffff0000, v98
	v_lshlrev_b32_e32 v68, 16, v99
	v_and_b32_e32 v69, 0xffff0000, v99
	v_mul_f32_e32 v6, v6, v176
	v_mul_f32_e32 v7, v7, v176
	v_mul_f32_e32 v8, v8, v176
	v_mul_f32_e32 v9, v9, v176
	v_mul_f32_e32 v6, v6, v116
	v_mul_f32_e32 v7, v7, v117
	v_mul_f32_e32 v8, v8, v118
	v_mul_f32_e32 v9, v9, v119
	v_mul_f32_e32 v6, v6, v66
	v_mul_f32_e32 v7, v7, v67
	v_mul_f32_e32 v8, v8, v68
	v_mul_f32_e32 v9, v9, v69
	v_cvt_pk_bf16_f32 v2, v2, v3
	v_cvt_pk_bf16_f32 v3, v4, v5
	v_cvt_pk_bf16_f32 v4, v6, v7
	v_cvt_pk_bf16_f32 v5, v8, v9
	global_store_dwordx4 v[120:121], v[2:5], off offset:2048
	v_lshlrev_b32_e32 v66, 16, v100
	v_and_b32_e32 v67, 0xffff0000, v100
	v_lshlrev_b32_e32 v68, 16, v101
	v_and_b32_e32 v69, 0xffff0000, v101
	v_mul_f32_e32 v10, v10, v177
	v_mul_f32_e32 v11, v11, v177
	v_mul_f32_e32 v12, v12, v177
	v_mul_f32_e32 v13, v13, v177
	v_mul_f32_e32 v10, v10, v112
	v_mul_f32_e32 v11, v11, v113
	v_mul_f32_e32 v12, v12, v114
	v_mul_f32_e32 v13, v13, v115
	v_mul_f32_e32 v10, v10, v66
	v_mul_f32_e32 v11, v11, v67
	v_mul_f32_e32 v12, v12, v68
	v_mul_f32_e32 v13, v13, v69
	v_lshlrev_b32_e32 v66, 16, v102
	v_and_b32_e32 v67, 0xffff0000, v102
	v_lshlrev_b32_e32 v68, 16, v103
	v_and_b32_e32 v69, 0xffff0000, v103
	v_mul_f32_e32 v14, v14, v177
	v_mul_f32_e32 v15, v15, v177
	v_mul_f32_e32 v16, v16, v177
	v_mul_f32_e32 v17, v17, v177
	v_mul_f32_e32 v14, v14, v116
	v_mul_f32_e32 v15, v15, v117
	v_mul_f32_e32 v16, v16, v118
	v_mul_f32_e32 v17, v17, v119
	v_mul_f32_e32 v14, v14, v66
	v_mul_f32_e32 v15, v15, v67
	v_mul_f32_e32 v16, v16, v68
	v_mul_f32_e32 v17, v17, v69
	v_cvt_pk_bf16_f32 v10, v10, v11
	v_cvt_pk_bf16_f32 v11, v12, v13
	v_cvt_pk_bf16_f32 v12, v14, v15
	v_cvt_pk_bf16_f32 v13, v16, v17
	global_store_dwordx4 v[122:123], v[10:13], off offset:2048
	v_lshlrev_b32_e32 v66, 16, v104
	v_and_b32_e32 v67, 0xffff0000, v104
	v_lshlrev_b32_e32 v68, 16, v105
	v_and_b32_e32 v69, 0xffff0000, v105
	v_mul_f32_e32 v18, v18, v86
	v_mul_f32_e32 v19, v19, v86
	v_mul_f32_e32 v20, v20, v86
	v_mul_f32_e32 v21, v21, v86
	v_mul_f32_e32 v18, v18, v112
	v_mul_f32_e32 v19, v19, v113
	v_mul_f32_e32 v20, v20, v114
	v_mul_f32_e32 v21, v21, v115
	v_mul_f32_e32 v18, v18, v66
	v_mul_f32_e32 v19, v19, v67
	v_mul_f32_e32 v20, v20, v68
	v_mul_f32_e32 v21, v21, v69
	v_lshlrev_b32_e32 v66, 16, v106
	v_and_b32_e32 v67, 0xffff0000, v106
	v_lshlrev_b32_e32 v68, 16, v107
	v_and_b32_e32 v69, 0xffff0000, v107
	v_mul_f32_e32 v22, v22, v86
	v_mul_f32_e32 v23, v23, v86
	v_mul_f32_e32 v24, v24, v86
	v_mul_f32_e32 v25, v25, v86
	v_mul_f32_e32 v22, v22, v116
	v_mul_f32_e32 v23, v23, v117
	v_mul_f32_e32 v24, v24, v118
	v_mul_f32_e32 v25, v25, v119
	v_mul_f32_e32 v22, v22, v66
	v_mul_f32_e32 v23, v23, v67
	v_mul_f32_e32 v24, v24, v68
	v_mul_f32_e32 v25, v25, v69
	v_cvt_pk_bf16_f32 v18, v18, v19
	v_cvt_pk_bf16_f32 v19, v20, v21
	v_cvt_pk_bf16_f32 v20, v22, v23
	v_cvt_pk_bf16_f32 v21, v24, v25
	global_store_dwordx4 v[124:125], v[18:21], off offset:2048
	v_lshlrev_b32_e32 v66, 16, v108
	v_and_b32_e32 v67, 0xffff0000, v108
	v_lshlrev_b32_e32 v68, 16, v109
	v_and_b32_e32 v69, 0xffff0000, v109
	v_mul_f32_e32 v26, v26, v87
	v_mul_f32_e32 v27, v27, v87
	v_mul_f32_e32 v28, v28, v87
	v_mul_f32_e32 v29, v29, v87
	v_mul_f32_e32 v26, v26, v112
	v_mul_f32_e32 v27, v27, v113
	v_mul_f32_e32 v28, v28, v114
	v_mul_f32_e32 v29, v29, v115
	v_mul_f32_e32 v26, v26, v66
	v_mul_f32_e32 v27, v27, v67
	v_mul_f32_e32 v28, v28, v68
	v_mul_f32_e32 v29, v29, v69
	v_lshlrev_b32_e32 v66, 16, v110
	v_and_b32_e32 v67, 0xffff0000, v110
	v_lshlrev_b32_e32 v68, 16, v111
	v_and_b32_e32 v69, 0xffff0000, v111
	v_mul_f32_e32 v30, v30, v87
	v_mul_f32_e32 v31, v31, v87
	v_mul_f32_e32 v32, v32, v87
	v_mul_f32_e32 v33, v33, v87
	v_mul_f32_e32 v30, v30, v116
	v_mul_f32_e32 v31, v31, v117
	v_mul_f32_e32 v32, v32, v118
	v_mul_f32_e32 v33, v33, v119
	v_mul_f32_e32 v30, v30, v66
	v_mul_f32_e32 v31, v31, v67
	v_mul_f32_e32 v32, v32, v68
	v_mul_f32_e32 v33, v33, v69
	v_cvt_pk_bf16_f32 v26, v26, v27
	v_cvt_pk_bf16_f32 v27, v28, v29
	v_cvt_pk_bf16_f32 v28, v30, v31
	v_cvt_pk_bf16_f32 v29, v32, v33
	global_store_dwordx4 v[126:127], v[26:29], off offset:2048
	s_branch .LBB0_1338
